# v44 + nt on the P2 residual epilogue's f32 x stores (next read is ~800 us later in P11)
# baseline (speedup 1.0000x reference)
.LBB0_930:
	s_or_b64 exec, exec, s[8:9]
	v_add_u32_e32 v131, 0xffffbc00, v162
	v_cmp_gt_i32_e64 s[8:9], s87, v162
	v_mov_b32_e32 v148, s27
	v_lshlrev_b64 v[164:165], 11, v[162:163]
	v_cndmask_b32_e64 v178, v131, v162, s[8:9]
	v_mov_b32_e32 v131, s63
	v_cndmask_b32_e64 v179, 0, v163, s[8:9]
	v_cndmask_b32_e64 v181, v131, v148, s[8:9]
	v_mov_b32_e32 v131, s62
	v_mov_b32_e32 v148, s26
	v_cndmask_b32_e64 v180, v131, v148, s[8:9]
	v_lshlrev_b64 v[178:179], 12, v[178:179]
	v_lshl_add_u64 v[178:179], v[180:181], 0, v[178:179]
	s_waitcnt vmcnt(0)
	v_pk_fma_f32 v[128:129], v[128:129], 0.5, v[138:139] op_sel_hi:[1,0,1]
	v_pk_fma_f32 v[126:127], v[126:127], 0.5, v[136:137] op_sel_hi:[1,0,1]
	v_pk_fma_f32 v[124:125], v[124:125], 0.5, v[134:135] op_sel_hi:[1,0,1]
	v_pk_fma_f32 v[122:123], v[122:123], 0.5, v[132:133] op_sel_hi:[1,0,1]
	v_lshl_add_u64 v[136:137], s[88:89], 0, v[164:165]
	v_lshl_add_u64 v[138:139], v[160:161], 2, v[178:179]
	v_cvt_pk_bf16_f32 v132, v126, v127
	v_cvt_pk_bf16_f32 v133, v128, v129
	v_cvt_pk_bf16_f32 v134, v122, v123
	v_cvt_pk_bf16_f32 v135, v124, v125
	v_lshl_add_u64 v[164:165], v[160:161], 1, v[136:137]
	global_store_dwordx4 v[138:139], v[126:129], off nt
	global_store_dwordx4 v[138:139], v[122:125], off offset:16 nt
	global_store_dwordx4 v[164:165], v[132:135], off
	v_mov_b32_e32 v131, 0
	v_mov_b32_e32 v136, 0
	v_mov_b32_e32 v132, 0
	v_mov_b32_e32 v133, 0
	v_mov_b32_e32 v134, 0
	v_mov_b32_e32 v135, 0
	v_mov_b32_e32 v137, 0
	s_and_saveexec_b64 s[8:9], vcc
	s_cbranch_execz .LBB0_932
	global_load_dwordx4 v[130:133], v[166:167], off offset:512 nt
	global_load_dwordx4 v[134:137], v[166:167], off offset:528 nt
.LBB0_932:
	s_or_b64 exec, exec, s[8:9]
	v_mul_f32_e32 v127, v127, v127
	v_mul_f32_e32 v123, v123, v123
	v_fmac_f32_e32 v127, v126, v126
	v_mul_f32_e32 v126, v129, v129
	v_fmac_f32_e32 v123, v122, v122
	v_mul_f32_e32 v122, v125, v125
	v_fmac_f32_e32 v126, v128, v128
	v_fmac_f32_e32 v122, v124, v124
	v_add_f32_e32 v126, v127, v126
	v_add_f32_e32 v122, v123, v122
	v_and_b32_e32 v123, 64, v177
	v_add_f32_e32 v126, v126, v122
	v_xor_b32_e32 v122, 16, v177
	v_add_u32_e32 v123, 64, v123
	v_cmp_lt_i32_e32 vcc, v122, v123
	s_waitcnt vmcnt(1)
	v_pk_fma_f32 v[120:121], v[120:121], 0.5, v[132:133] op_sel_hi:[1,0,1]
	v_pk_fma_f32 v[118:119], v[118:119], 0.5, v[130:131] op_sel_hi:[1,0,1]
	v_cndmask_b32_e32 v122, v177, v122, vcc
	v_lshlrev_b32_e32 v167, 2, v122
	v_xor_b32_e32 v122, 32, v177
	v_cmp_lt_i32_e32 vcc, v122, v123
	s_waitcnt vmcnt(0)
	v_pk_fma_f32 v[124:125], v[116:117], 0.5, v[136:137] op_sel_hi:[1,0,1]
	s_lshl_b32 s70, s14, 2
	v_cndmask_b32_e32 v122, v177, v122, vcc
	v_lshlrev_b32_e32 v166, 2, v122
	v_pk_fma_f32 v[122:123], v[114:115], 0.5, v[134:135] op_sel_hi:[1,0,1]
	v_mul_f32_e32 v114, v119, v119
	v_mul_f32_e32 v115, v121, v121
	v_fmac_f32_e32 v114, v118, v118
	v_fmac_f32_e32 v115, v120, v120
	v_add_f32_e32 v114, v114, v115
	v_mul_f32_e32 v115, v123, v123
	v_mul_f32_e32 v116, v125, v125
	v_fmac_f32_e32 v115, v122, v122
	v_fmac_f32_e32 v116, v124, v124
	v_add_f32_e32 v115, v115, v116
	v_add_f32_e32 v114, v114, v115
	v_add_f32_e32 v114, v126, v114
	ds_bpermute_b32 v115, v167, v114
	s_ashr_i32 s71, s70, 31
	global_store_dwordx4 v[138:139], v[118:121], off offset:512 nt
	global_store_dwordx4 v[138:139], v[122:125], off offset:528 nt
	v_cvt_pk_bf16_f32 v116, v118, v119
	v_cvt_pk_bf16_f32 v117, v120, v121
	s_waitcnt lgkmcnt(0)
	v_add_f32_e32 v114, v114, v115
	ds_bpermute_b32 v115, v166, v114
	v_cvt_pk_bf16_f32 v118, v122, v123
	v_cvt_pk_bf16_f32 v119, v124, v125
	global_store_dwordx4 v[164:165], v[116:119], off offset:256
	s_and_saveexec_b64 s[8:9], s[4:5]
	s_cbranch_execz .LBB0_934
	v_lshlrev_b64 v[116:117], 6, v[162:163]
	v_lshl_add_u64 v[116:117], s[76:77], 0, v[116:117]
	v_lshl_add_u64 v[116:117], s[70:71], 2, v[116:117]
	s_lshl_b32 s14, s56, 2
	v_lshl_add_u64 v[116:117], v[116:117], 0, s[14:15]
	s_waitcnt lgkmcnt(0)
	v_add_f32_e32 v114, v114, v115
	global_store_dword v[116:117], v114, off

.LBB0_943:
	s_or_b64 exec, exec, s[8:9]
	s_waitcnt lgkmcnt(0)
	v_add_u32_e32 v115, 0xffffbc10, v162
	v_cmp_gt_i32_e64 s[8:9], s87, v124
	v_mov_b32_e32 v132, s27
	v_lshlrev_b64 v[126:127], 11, v[124:125]
	v_cndmask_b32_e64 v130, v115, v124, s[8:9]
	v_mov_b32_e32 v115, s63
	v_cndmask_b32_e64 v131, 0, v125, s[8:9]
	v_cndmask_b32_e64 v133, v115, v132, s[8:9]
	v_mov_b32_e32 v115, s62
	v_mov_b32_e32 v132, s26
	v_cndmask_b32_e64 v132, v115, v132, s[8:9]
	v_lshlrev_b64 v[130:131], 12, v[130:131]
	v_lshl_add_u64 v[130:131], v[132:133], 0, v[130:131]
	s_waitcnt vmcnt(1)
	v_pk_fma_f32 v[112:113], v[112:113], 0.5, v[122:123] op_sel_hi:[1,0,1]
	v_pk_fma_f32 v[110:111], v[110:111], 0.5, v[120:121] op_sel_hi:[1,0,1]
	s_waitcnt vmcnt(0)
	v_pk_fma_f32 v[108:109], v[108:109], 0.5, v[118:119] op_sel_hi:[1,0,1]
	v_pk_fma_f32 v[106:107], v[106:107], 0.5, v[116:117] op_sel_hi:[1,0,1]
	v_lshl_add_u64 v[120:121], s[88:89], 0, v[126:127]
	v_lshl_add_u64 v[122:123], v[160:161], 2, v[130:131]
	v_cvt_pk_bf16_f32 v116, v110, v111
	v_cvt_pk_bf16_f32 v117, v112, v113
	v_cvt_pk_bf16_f32 v118, v106, v107
	v_cvt_pk_bf16_f32 v119, v108, v109
	v_lshl_add_u64 v[126:127], v[160:161], 1, v[120:121]
	global_store_dwordx4 v[122:123], v[110:113], off nt
	global_store_dwordx4 v[122:123], v[106:109], off offset:16 nt
	global_store_dwordx4 v[126:127], v[116:119], off
	v_mov_b32_e32 v115, 0
	v_mov_b32_e32 v120, 0
	v_mov_b32_e32 v116, 0
	v_mov_b32_e32 v117, 0
	v_mov_b32_e32 v118, 0
	v_mov_b32_e32 v119, 0
	v_mov_b32_e32 v121, 0
	s_and_saveexec_b64 s[8:9], vcc
	s_cbranch_execz .LBB0_945
	global_load_dwordx4 v[114:117], v[128:129], off offset:512 nt
	global_load_dwordx4 v[118:121], v[128:129], off offset:528 nt
.LBB0_945:
	s_or_b64 exec, exec, s[8:9]
	v_mul_f32_e32 v111, v111, v111
	v_mul_f32_e32 v107, v107, v107
	v_fmac_f32_e32 v111, v110, v110
	v_mul_f32_e32 v110, v113, v113
	v_fmac_f32_e32 v107, v106, v106
	v_mul_f32_e32 v106, v109, v109
	v_fmac_f32_e32 v110, v112, v112
	v_fmac_f32_e32 v106, v108, v108
	v_add_f32_e32 v110, v111, v110
	v_add_f32_e32 v106, v107, v106
	s_waitcnt vmcnt(1)
	v_pk_fma_f32 v[104:105], v[104:105], 0.5, v[116:117] op_sel_hi:[1,0,1]
	v_pk_fma_f32 v[102:103], v[102:103], 0.5, v[114:115] op_sel_hi:[1,0,1]
	v_add_f32_e32 v110, v110, v106
	s_waitcnt vmcnt(0)
	v_pk_fma_f32 v[106:107], v[98:99], 0.5, v[118:119] op_sel_hi:[1,0,1]
	v_mul_f32_e32 v98, v103, v103
	v_mul_f32_e32 v99, v105, v105
	v_pk_fma_f32 v[108:109], v[100:101], 0.5, v[120:121] op_sel_hi:[1,0,1]
	v_fmac_f32_e32 v98, v102, v102
	v_fmac_f32_e32 v99, v104, v104
	v_add_f32_e32 v98, v98, v99
	v_mul_f32_e32 v99, v107, v107
	v_mul_f32_e32 v100, v109, v109
	v_fmac_f32_e32 v99, v106, v106
	v_fmac_f32_e32 v100, v108, v108
	v_add_f32_e32 v99, v99, v100
	v_add_f32_e32 v98, v98, v99
	v_add_f32_e32 v98, v110, v98
	ds_bpermute_b32 v99, v167, v98
	global_store_dwordx4 v[122:123], v[102:105], off offset:512 nt
	global_store_dwordx4 v[122:123], v[106:109], off offset:528 nt
	v_cvt_pk_bf16_f32 v100, v102, v103
	v_cvt_pk_bf16_f32 v101, v104, v105
	v_cvt_pk_bf16_f32 v102, v106, v107
	s_waitcnt lgkmcnt(0)
	v_add_f32_e32 v98, v98, v99
	ds_bpermute_b32 v99, v166, v98
	v_cvt_pk_bf16_f32 v103, v108, v109
	global_store_dwordx4 v[126:127], v[100:103], off offset:256
	s_and_saveexec_b64 s[8:9], s[4:5]
	s_cbranch_execz .LBB0_947
	v_lshlrev_b64 v[100:101], 6, v[124:125]
	v_lshl_add_u64 v[100:101], s[76:77], 0, v[100:101]
	v_lshl_add_u64 v[100:101], s[70:71], 2, v[100:101]
	s_lshl_b32 s14, s56, 2
	v_lshl_add_u64 v[100:101], v[100:101], 0, s[14:15]
	s_waitcnt lgkmcnt(0)
	v_add_f32_e32 v98, v98, v99
	global_store_dword v[100:101], v98, off

.LBB0_956:
	s_or_b64 exec, exec, s[8:9]
	s_waitcnt lgkmcnt(0)
	v_add_u32_e32 v99, 0xffffbc20, v162
	v_cmp_gt_i32_e64 s[8:9], s87, v108
	v_mov_b32_e32 v116, s27
	v_lshlrev_b64 v[110:111], 11, v[108:109]
	v_cndmask_b32_e64 v114, v99, v108, s[8:9]
	v_mov_b32_e32 v99, s63
	v_cndmask_b32_e64 v115, 0, v109, s[8:9]
	v_cndmask_b32_e64 v117, v99, v116, s[8:9]
	v_mov_b32_e32 v99, s62
	v_mov_b32_e32 v116, s26
	v_cndmask_b32_e64 v116, v99, v116, s[8:9]
	v_lshlrev_b64 v[114:115], 12, v[114:115]
	v_lshl_add_u64 v[114:115], v[116:117], 0, v[114:115]
	s_waitcnt vmcnt(1)
	v_pk_fma_f32 v[96:97], v[96:97], 0.5, v[106:107] op_sel_hi:[1,0,1]
	v_pk_fma_f32 v[94:95], v[94:95], 0.5, v[104:105] op_sel_hi:[1,0,1]
	s_waitcnt vmcnt(0)
	v_pk_fma_f32 v[92:93], v[92:93], 0.5, v[102:103] op_sel_hi:[1,0,1]
	v_pk_fma_f32 v[90:91], v[90:91], 0.5, v[100:101] op_sel_hi:[1,0,1]
	v_lshl_add_u64 v[104:105], s[88:89], 0, v[110:111]
	v_lshl_add_u64 v[106:107], v[160:161], 2, v[114:115]
	v_cvt_pk_bf16_f32 v100, v94, v95
	v_cvt_pk_bf16_f32 v101, v96, v97
	v_cvt_pk_bf16_f32 v102, v90, v91
	v_cvt_pk_bf16_f32 v103, v92, v93
	v_lshl_add_u64 v[110:111], v[160:161], 1, v[104:105]
	global_store_dwordx4 v[106:107], v[94:97], off nt
	global_store_dwordx4 v[106:107], v[90:93], off offset:16 nt
	global_store_dwordx4 v[110:111], v[100:103], off
	v_mov_b32_e32 v99, 0
	v_mov_b32_e32 v104, 0
	v_mov_b32_e32 v100, 0
	v_mov_b32_e32 v101, 0
	v_mov_b32_e32 v102, 0
	v_mov_b32_e32 v103, 0
	v_mov_b32_e32 v105, 0
	s_and_saveexec_b64 s[8:9], vcc
	s_cbranch_execz .LBB0_958
	global_load_dwordx4 v[98:101], v[112:113], off offset:512 nt
	global_load_dwordx4 v[102:105], v[112:113], off offset:528 nt
.LBB0_958:
	s_or_b64 exec, exec, s[8:9]
	v_mul_f32_e32 v95, v95, v95
	v_mul_f32_e32 v91, v91, v91
	v_fmac_f32_e32 v95, v94, v94
	v_mul_f32_e32 v94, v97, v97
	v_fmac_f32_e32 v91, v90, v90
	v_mul_f32_e32 v90, v93, v93
	v_fmac_f32_e32 v94, v96, v96
	v_fmac_f32_e32 v90, v92, v92
	v_add_f32_e32 v94, v95, v94
	v_add_f32_e32 v90, v91, v90
	s_waitcnt vmcnt(1)
	v_pk_fma_f32 v[88:89], v[88:89], 0.5, v[100:101] op_sel_hi:[1,0,1]
	v_pk_fma_f32 v[86:87], v[86:87], 0.5, v[98:99] op_sel_hi:[1,0,1]
	v_add_f32_e32 v94, v94, v90
	s_waitcnt vmcnt(0)
	v_pk_fma_f32 v[90:91], v[82:83], 0.5, v[102:103] op_sel_hi:[1,0,1]
	v_mul_f32_e32 v82, v87, v87
	v_mul_f32_e32 v83, v89, v89
	v_pk_fma_f32 v[92:93], v[84:85], 0.5, v[104:105] op_sel_hi:[1,0,1]
	v_fmac_f32_e32 v82, v86, v86
	v_fmac_f32_e32 v83, v88, v88
	v_add_f32_e32 v82, v82, v83
	v_mul_f32_e32 v83, v91, v91
	v_mul_f32_e32 v84, v93, v93
	v_fmac_f32_e32 v83, v90, v90
	v_fmac_f32_e32 v84, v92, v92
	v_add_f32_e32 v83, v83, v84
	v_add_f32_e32 v82, v82, v83
	v_add_f32_e32 v82, v94, v82
	ds_bpermute_b32 v83, v167, v82
	global_store_dwordx4 v[106:107], v[86:89], off offset:512 nt
	global_store_dwordx4 v[106:107], v[90:93], off offset:528 nt
	v_cvt_pk_bf16_f32 v84, v86, v87
	v_cvt_pk_bf16_f32 v85, v88, v89
	v_cvt_pk_bf16_f32 v86, v90, v91
	s_waitcnt lgkmcnt(0)
	v_add_f32_e32 v82, v82, v83
	ds_bpermute_b32 v83, v166, v82
	v_cvt_pk_bf16_f32 v87, v92, v93
	global_store_dwordx4 v[110:111], v[84:87], off offset:256
	s_and_saveexec_b64 s[8:9], s[4:5]
	s_cbranch_execz .LBB0_960
	v_lshlrev_b64 v[84:85], 6, v[108:109]
	v_lshl_add_u64 v[84:85], s[76:77], 0, v[84:85]
	v_lshl_add_u64 v[84:85], s[70:71], 2, v[84:85]
	s_lshl_b32 s14, s56, 2
	v_lshl_add_u64 v[84:85], v[84:85], 0, s[14:15]
	s_waitcnt lgkmcnt(0)
	v_add_f32_e32 v82, v82, v83
	global_store_dword v[84:85], v82, off

.LBB0_969:
	s_or_b64 exec, exec, s[8:9]
	s_waitcnt lgkmcnt(0)
	v_add_u32_e32 v83, 0xffffbc30, v162
	v_cmp_gt_i32_e64 s[8:9], s87, v92
	v_mov_b32_e32 v100, s27
	v_lshlrev_b64 v[94:95], 11, v[92:93]
	v_cndmask_b32_e64 v98, v83, v92, s[8:9]
	v_mov_b32_e32 v83, s63
	v_cndmask_b32_e64 v99, 0, v93, s[8:9]
	v_cndmask_b32_e64 v101, v83, v100, s[8:9]
	v_mov_b32_e32 v83, s62
	v_mov_b32_e32 v100, s26
	v_cndmask_b32_e64 v100, v83, v100, s[8:9]
	v_lshlrev_b64 v[98:99], 12, v[98:99]
	v_lshl_add_u64 v[98:99], v[100:101], 0, v[98:99]
	s_waitcnt vmcnt(1)
	v_pk_fma_f32 v[80:81], v[80:81], 0.5, v[90:91] op_sel_hi:[1,0,1]
	v_pk_fma_f32 v[78:79], v[78:79], 0.5, v[88:89] op_sel_hi:[1,0,1]
	s_waitcnt vmcnt(0)
	v_pk_fma_f32 v[76:77], v[76:77], 0.5, v[86:87] op_sel_hi:[1,0,1]
	v_pk_fma_f32 v[74:75], v[74:75], 0.5, v[84:85] op_sel_hi:[1,0,1]
	v_lshl_add_u64 v[88:89], s[88:89], 0, v[94:95]
	v_lshl_add_u64 v[90:91], v[160:161], 2, v[98:99]
	v_cvt_pk_bf16_f32 v84, v78, v79
	v_cvt_pk_bf16_f32 v85, v80, v81
	v_cvt_pk_bf16_f32 v86, v74, v75
	v_cvt_pk_bf16_f32 v87, v76, v77
	v_lshl_add_u64 v[94:95], v[160:161], 1, v[88:89]
	global_store_dwordx4 v[90:91], v[78:81], off nt
	global_store_dwordx4 v[90:91], v[74:77], off offset:16 nt
	global_store_dwordx4 v[94:95], v[84:87], off
	v_mov_b32_e32 v83, 0
	v_mov_b32_e32 v88, 0
	v_mov_b32_e32 v84, 0
	v_mov_b32_e32 v85, 0
	v_mov_b32_e32 v86, 0
	v_mov_b32_e32 v87, 0
	v_mov_b32_e32 v89, 0
	s_and_saveexec_b64 s[8:9], vcc
	s_cbranch_execz .LBB0_971
	global_load_dwordx4 v[82:85], v[96:97], off offset:512 nt
	global_load_dwordx4 v[86:89], v[96:97], off offset:528 nt
.LBB0_971:
	s_or_b64 exec, exec, s[8:9]
	v_mul_f32_e32 v79, v79, v79
	v_mul_f32_e32 v75, v75, v75
	v_fmac_f32_e32 v79, v78, v78
	v_mul_f32_e32 v78, v81, v81
	v_fmac_f32_e32 v75, v74, v74
	v_mul_f32_e32 v74, v77, v77
	v_fmac_f32_e32 v78, v80, v80
	v_fmac_f32_e32 v74, v76, v76
	v_add_f32_e32 v78, v79, v78
	v_add_f32_e32 v74, v75, v74
	s_waitcnt vmcnt(1)
	v_pk_fma_f32 v[72:73], v[72:73], 0.5, v[84:85] op_sel_hi:[1,0,1]
	v_pk_fma_f32 v[70:71], v[70:71], 0.5, v[82:83] op_sel_hi:[1,0,1]
	v_add_f32_e32 v78, v78, v74
	s_waitcnt vmcnt(0)
	v_pk_fma_f32 v[74:75], v[66:67], 0.5, v[86:87] op_sel_hi:[1,0,1]
	v_mul_f32_e32 v66, v71, v71
	v_mul_f32_e32 v67, v73, v73
	v_pk_fma_f32 v[76:77], v[68:69], 0.5, v[88:89] op_sel_hi:[1,0,1]
	v_fmac_f32_e32 v66, v70, v70
	v_fmac_f32_e32 v67, v72, v72
	v_add_f32_e32 v66, v66, v67
	v_mul_f32_e32 v67, v75, v75
	v_mul_f32_e32 v68, v77, v77
	v_fmac_f32_e32 v67, v74, v74
	v_fmac_f32_e32 v68, v76, v76
	v_add_f32_e32 v67, v67, v68
	v_add_f32_e32 v66, v66, v67
	v_add_f32_e32 v66, v78, v66
	ds_bpermute_b32 v67, v167, v66
	global_store_dwordx4 v[90:91], v[70:73], off offset:512 nt
	global_store_dwordx4 v[90:91], v[74:77], off offset:528 nt
	v_cvt_pk_bf16_f32 v68, v70, v71
	v_cvt_pk_bf16_f32 v69, v72, v73
	v_cvt_pk_bf16_f32 v70, v74, v75
	s_waitcnt lgkmcnt(0)
	v_add_f32_e32 v66, v66, v67
	ds_bpermute_b32 v67, v166, v66
	v_cvt_pk_bf16_f32 v71, v76, v77
	global_store_dwordx4 v[94:95], v[68:71], off offset:256
	s_and_saveexec_b64 s[8:9], s[4:5]
	s_cbranch_execz .LBB0_973
	v_lshlrev_b64 v[68:69], 6, v[92:93]
	v_lshl_add_u64 v[68:69], s[76:77], 0, v[68:69]
	v_lshl_add_u64 v[68:69], s[70:71], 2, v[68:69]
	s_lshl_b32 s14, s56, 2
	v_lshl_add_u64 v[68:69], v[68:69], 0, s[14:15]
	s_waitcnt lgkmcnt(0)
	v_add_f32_e32 v66, v66, v67
	global_store_dword v[68:69], v66, off

.LBB0_982:
	s_or_b64 exec, exec, s[8:9]
	s_waitcnt lgkmcnt(0)
	v_add_u32_e32 v67, 0xffffbc00, v76
	v_cmp_gt_i32_e64 s[8:9], s87, v76
	v_mov_b32_e32 v84, s27
	v_lshlrev_b64 v[78:79], 11, v[76:77]
	v_cndmask_b32_e64 v82, v67, v76, s[8:9]
	v_mov_b32_e32 v67, s63
	v_cndmask_b32_e64 v83, 0, v77, s[8:9]
	v_cndmask_b32_e64 v85, v67, v84, s[8:9]
	v_mov_b32_e32 v67, s62
	v_mov_b32_e32 v84, s26
	v_cndmask_b32_e64 v84, v67, v84, s[8:9]
	v_lshlrev_b64 v[82:83], 12, v[82:83]
	v_lshl_add_u64 v[82:83], v[84:85], 0, v[82:83]
	s_waitcnt vmcnt(1)
	v_pk_fma_f32 v[64:65], v[64:65], 0.5, v[74:75] op_sel_hi:[1,0,1]
	v_pk_fma_f32 v[62:63], v[62:63], 0.5, v[72:73] op_sel_hi:[1,0,1]
	s_waitcnt vmcnt(0)
	v_pk_fma_f32 v[60:61], v[60:61], 0.5, v[70:71] op_sel_hi:[1,0,1]
	v_pk_fma_f32 v[58:59], v[58:59], 0.5, v[68:69] op_sel_hi:[1,0,1]
	v_lshl_add_u64 v[72:73], s[88:89], 0, v[78:79]
	v_lshl_add_u64 v[74:75], v[160:161], 2, v[82:83]
	v_cvt_pk_bf16_f32 v68, v62, v63
	v_cvt_pk_bf16_f32 v69, v64, v65
	v_cvt_pk_bf16_f32 v70, v58, v59
	v_cvt_pk_bf16_f32 v71, v60, v61
	v_lshl_add_u64 v[78:79], v[160:161], 1, v[72:73]
	global_store_dwordx4 v[74:75], v[62:65], off nt
	global_store_dwordx4 v[74:75], v[58:61], off offset:16 nt
	global_store_dwordx4 v[78:79], v[68:71], off
	v_mov_b32_e32 v67, 0
	v_mov_b32_e32 v72, 0
	v_mov_b32_e32 v68, 0
	v_mov_b32_e32 v69, 0
	v_mov_b32_e32 v70, 0
	v_mov_b32_e32 v71, 0
	v_mov_b32_e32 v73, 0
	s_and_saveexec_b64 s[8:9], vcc
	s_cbranch_execz .LBB0_984
	global_load_dwordx4 v[66:69], v[80:81], off offset:512 nt
	global_load_dwordx4 v[70:73], v[80:81], off offset:528 nt
.LBB0_984:
	s_or_b64 exec, exec, s[8:9]
	v_mul_f32_e32 v63, v63, v63
	v_mul_f32_e32 v59, v59, v59
	v_fmac_f32_e32 v63, v62, v62
	v_mul_f32_e32 v62, v65, v65
	v_fmac_f32_e32 v59, v58, v58
	v_mul_f32_e32 v58, v61, v61
	v_fmac_f32_e32 v62, v64, v64
	v_fmac_f32_e32 v58, v60, v60
	v_add_f32_e32 v62, v63, v62
	v_add_f32_e32 v58, v59, v58
	s_waitcnt vmcnt(1)
	v_pk_fma_f32 v[56:57], v[56:57], 0.5, v[68:69] op_sel_hi:[1,0,1]
	v_pk_fma_f32 v[54:55], v[54:55], 0.5, v[66:67] op_sel_hi:[1,0,1]
	v_add_f32_e32 v62, v62, v58
	s_waitcnt vmcnt(0)
	v_pk_fma_f32 v[58:59], v[50:51], 0.5, v[70:71] op_sel_hi:[1,0,1]
	v_mul_f32_e32 v50, v55, v55
	v_mul_f32_e32 v51, v57, v57
	v_pk_fma_f32 v[60:61], v[52:53], 0.5, v[72:73] op_sel_hi:[1,0,1]
	v_fmac_f32_e32 v50, v54, v54
	v_fmac_f32_e32 v51, v56, v56
	v_add_f32_e32 v50, v50, v51
	v_mul_f32_e32 v51, v59, v59
	v_mul_f32_e32 v52, v61, v61
	v_fmac_f32_e32 v51, v58, v58
	v_fmac_f32_e32 v52, v60, v60
	v_add_f32_e32 v51, v51, v52
	v_add_f32_e32 v50, v50, v51
	v_add_f32_e32 v50, v62, v50
	ds_bpermute_b32 v51, v167, v50
	global_store_dwordx4 v[74:75], v[54:57], off offset:512 nt
	global_store_dwordx4 v[74:75], v[58:61], off offset:528 nt
	v_cvt_pk_bf16_f32 v52, v54, v55
	v_cvt_pk_bf16_f32 v53, v56, v57
	v_cvt_pk_bf16_f32 v54, v58, v59
	s_waitcnt lgkmcnt(0)
	v_add_f32_e32 v50, v50, v51
	ds_bpermute_b32 v51, v166, v50
	v_cvt_pk_bf16_f32 v55, v60, v61
	global_store_dwordx4 v[78:79], v[52:55], off offset:256
	s_and_saveexec_b64 s[8:9], s[4:5]
	s_cbranch_execz .LBB0_986
	v_lshlrev_b64 v[52:53], 6, v[76:77]
	v_lshl_add_u64 v[52:53], s[76:77], 0, v[52:53]
	v_lshl_add_u64 v[52:53], s[70:71], 2, v[52:53]
	s_lshl_b32 s14, s56, 2
	v_lshl_add_u64 v[52:53], v[52:53], 0, s[14:15]
	s_waitcnt lgkmcnt(0)
	v_add_f32_e32 v50, v50, v51
	global_store_dword v[52:53], v50, off

.LBB0_995:
	s_or_b64 exec, exec, s[8:9]
	s_waitcnt lgkmcnt(0)
	v_add_u32_e32 v51, 0xffffbc00, v60
	v_cmp_gt_i32_e64 s[8:9], s87, v60
	v_mov_b32_e32 v68, s27
	v_lshlrev_b64 v[62:63], 11, v[60:61]
	v_cndmask_b32_e64 v66, v51, v60, s[8:9]
	v_mov_b32_e32 v51, s63
	v_cndmask_b32_e64 v67, 0, v61, s[8:9]
	v_cndmask_b32_e64 v69, v51, v68, s[8:9]
	v_mov_b32_e32 v51, s62
	v_mov_b32_e32 v68, s26
	v_cndmask_b32_e64 v68, v51, v68, s[8:9]
	v_lshlrev_b64 v[66:67], 12, v[66:67]
	v_lshl_add_u64 v[66:67], v[68:69], 0, v[66:67]
	s_waitcnt vmcnt(1)
	v_pk_fma_f32 v[48:49], v[48:49], 0.5, v[58:59] op_sel_hi:[1,0,1]
	v_pk_fma_f32 v[46:47], v[46:47], 0.5, v[56:57] op_sel_hi:[1,0,1]
	s_waitcnt vmcnt(0)
	v_pk_fma_f32 v[44:45], v[44:45], 0.5, v[54:55] op_sel_hi:[1,0,1]
	v_pk_fma_f32 v[42:43], v[42:43], 0.5, v[52:53] op_sel_hi:[1,0,1]
	v_lshl_add_u64 v[56:57], s[88:89], 0, v[62:63]
	v_lshl_add_u64 v[58:59], v[160:161], 2, v[66:67]
	v_cvt_pk_bf16_f32 v52, v46, v47
	v_cvt_pk_bf16_f32 v53, v48, v49
	v_cvt_pk_bf16_f32 v54, v42, v43
	v_cvt_pk_bf16_f32 v55, v44, v45
	v_lshl_add_u64 v[62:63], v[160:161], 1, v[56:57]
	global_store_dwordx4 v[58:59], v[46:49], off nt
	global_store_dwordx4 v[58:59], v[42:45], off offset:16 nt
	global_store_dwordx4 v[62:63], v[52:55], off
	v_mov_b32_e32 v51, 0
	v_mov_b32_e32 v56, 0
	v_mov_b32_e32 v52, 0
	v_mov_b32_e32 v53, 0
	v_mov_b32_e32 v54, 0
	v_mov_b32_e32 v55, 0
	v_mov_b32_e32 v57, 0
	s_and_saveexec_b64 s[8:9], vcc
	s_cbranch_execz .LBB0_997
	global_load_dwordx4 v[50:53], v[64:65], off offset:512 nt
	global_load_dwordx4 v[54:57], v[64:65], off offset:528 nt
.LBB0_997:
	s_or_b64 exec, exec, s[8:9]
	v_mul_f32_e32 v47, v47, v47
	v_mul_f32_e32 v43, v43, v43
	v_fmac_f32_e32 v47, v46, v46
	v_mul_f32_e32 v46, v49, v49
	v_fmac_f32_e32 v43, v42, v42
	v_mul_f32_e32 v42, v45, v45
	v_fmac_f32_e32 v46, v48, v48
	v_fmac_f32_e32 v42, v44, v44
	v_add_f32_e32 v46, v47, v46
	v_add_f32_e32 v42, v43, v42
	s_waitcnt vmcnt(1)
	v_pk_fma_f32 v[40:41], v[40:41], 0.5, v[52:53] op_sel_hi:[1,0,1]
	v_pk_fma_f32 v[38:39], v[38:39], 0.5, v[50:51] op_sel_hi:[1,0,1]
	v_add_f32_e32 v46, v46, v42
	s_waitcnt vmcnt(0)
	v_pk_fma_f32 v[42:43], v[34:35], 0.5, v[54:55] op_sel_hi:[1,0,1]
	v_mul_f32_e32 v34, v39, v39
	v_mul_f32_e32 v35, v41, v41
	v_pk_fma_f32 v[44:45], v[36:37], 0.5, v[56:57] op_sel_hi:[1,0,1]
	v_fmac_f32_e32 v34, v38, v38
	v_fmac_f32_e32 v35, v40, v40
	v_add_f32_e32 v34, v34, v35
	v_mul_f32_e32 v35, v43, v43
	v_mul_f32_e32 v36, v45, v45
	v_fmac_f32_e32 v35, v42, v42
	v_fmac_f32_e32 v36, v44, v44
	v_add_f32_e32 v35, v35, v36
	v_add_f32_e32 v34, v34, v35
	v_add_f32_e32 v34, v46, v34
	ds_bpermute_b32 v35, v167, v34
	global_store_dwordx4 v[58:59], v[38:41], off offset:512 nt
	global_store_dwordx4 v[58:59], v[42:45], off offset:528 nt
	v_cvt_pk_bf16_f32 v36, v38, v39
	v_cvt_pk_bf16_f32 v37, v40, v41
	v_cvt_pk_bf16_f32 v38, v42, v43
	s_waitcnt lgkmcnt(0)
	v_add_f32_e32 v34, v34, v35
	ds_bpermute_b32 v35, v166, v34
	v_cvt_pk_bf16_f32 v39, v44, v45
	global_store_dwordx4 v[62:63], v[36:39], off offset:256
	s_and_saveexec_b64 s[8:9], s[4:5]
	s_cbranch_execz .LBB0_999
	v_lshlrev_b64 v[36:37], 6, v[60:61]
	v_lshl_add_u64 v[36:37], s[76:77], 0, v[36:37]
	v_lshl_add_u64 v[36:37], s[70:71], 2, v[36:37]
	s_lshl_b32 s14, s56, 2
	v_lshl_add_u64 v[36:37], v[36:37], 0, s[14:15]
	s_waitcnt lgkmcnt(0)
	v_add_f32_e32 v34, v34, v35
	global_store_dword v[36:37], v34, off

.LBB0_1008:
	s_or_b64 exec, exec, s[8:9]
	s_waitcnt lgkmcnt(0)
	v_add_u32_e32 v35, 0xffffbc00, v44
	v_cmp_gt_i32_e64 s[8:9], s87, v44
	v_mov_b32_e32 v52, s27
	v_lshlrev_b64 v[46:47], 11, v[44:45]
	v_cndmask_b32_e64 v50, v35, v44, s[8:9]
	v_mov_b32_e32 v35, s63
	v_cndmask_b32_e64 v51, 0, v45, s[8:9]
	v_cndmask_b32_e64 v53, v35, v52, s[8:9]
	v_mov_b32_e32 v35, s62
	v_mov_b32_e32 v52, s26
	v_cndmask_b32_e64 v52, v35, v52, s[8:9]
	v_lshlrev_b64 v[50:51], 12, v[50:51]
	v_lshl_add_u64 v[50:51], v[52:53], 0, v[50:51]
	s_waitcnt vmcnt(1)
	v_pk_fma_f32 v[32:33], v[32:33], 0.5, v[42:43] op_sel_hi:[1,0,1]
	v_pk_fma_f32 v[30:31], v[30:31], 0.5, v[40:41] op_sel_hi:[1,0,1]
	s_waitcnt vmcnt(0)
	v_pk_fma_f32 v[28:29], v[28:29], 0.5, v[38:39] op_sel_hi:[1,0,1]
	v_pk_fma_f32 v[26:27], v[26:27], 0.5, v[36:37] op_sel_hi:[1,0,1]
	v_lshl_add_u64 v[40:41], s[88:89], 0, v[46:47]
	v_lshl_add_u64 v[42:43], v[160:161], 2, v[50:51]
	v_cvt_pk_bf16_f32 v36, v30, v31
	v_cvt_pk_bf16_f32 v37, v32, v33
	v_cvt_pk_bf16_f32 v38, v26, v27
	v_cvt_pk_bf16_f32 v39, v28, v29
	v_lshl_add_u64 v[46:47], v[160:161], 1, v[40:41]
	global_store_dwordx4 v[42:43], v[30:33], off nt
	global_store_dwordx4 v[42:43], v[26:29], off offset:16 nt
	global_store_dwordx4 v[46:47], v[36:39], off
	v_mov_b32_e32 v35, 0
	v_mov_b32_e32 v40, 0
	v_mov_b32_e32 v36, 0
	v_mov_b32_e32 v37, 0
	v_mov_b32_e32 v38, 0
	v_mov_b32_e32 v39, 0
	v_mov_b32_e32 v41, 0
	s_and_saveexec_b64 s[8:9], vcc
	s_cbranch_execz .LBB0_1010
	global_load_dwordx4 v[34:37], v[48:49], off offset:512 nt
	global_load_dwordx4 v[38:41], v[48:49], off offset:528 nt
.LBB0_1010:
	s_or_b64 exec, exec, s[8:9]
	v_mul_f32_e32 v31, v31, v31
	v_mul_f32_e32 v27, v27, v27
	v_fmac_f32_e32 v31, v30, v30
	v_mul_f32_e32 v30, v33, v33
	v_fmac_f32_e32 v27, v26, v26
	v_mul_f32_e32 v26, v29, v29
	v_fmac_f32_e32 v30, v32, v32
	v_fmac_f32_e32 v26, v28, v28
	v_add_f32_e32 v30, v31, v30
	v_add_f32_e32 v26, v27, v26
	s_waitcnt vmcnt(1)
	v_pk_fma_f32 v[24:25], v[24:25], 0.5, v[36:37] op_sel_hi:[1,0,1]
	v_pk_fma_f32 v[22:23], v[22:23], 0.5, v[34:35] op_sel_hi:[1,0,1]
	v_add_f32_e32 v30, v30, v26
	s_waitcnt vmcnt(0)
	v_pk_fma_f32 v[26:27], v[18:19], 0.5, v[38:39] op_sel_hi:[1,0,1]
	v_mul_f32_e32 v18, v23, v23
	v_mul_f32_e32 v19, v25, v25
	v_pk_fma_f32 v[28:29], v[20:21], 0.5, v[40:41] op_sel_hi:[1,0,1]
	v_fmac_f32_e32 v18, v22, v22
	v_fmac_f32_e32 v19, v24, v24
	v_add_f32_e32 v18, v18, v19
	v_mul_f32_e32 v19, v27, v27
	v_mul_f32_e32 v20, v29, v29
	v_fmac_f32_e32 v19, v26, v26
	v_fmac_f32_e32 v20, v28, v28
	v_add_f32_e32 v19, v19, v20
	v_add_f32_e32 v18, v18, v19
	v_add_f32_e32 v18, v30, v18
	ds_bpermute_b32 v19, v167, v18
	global_store_dwordx4 v[42:43], v[22:25], off offset:512 nt
	global_store_dwordx4 v[42:43], v[26:29], off offset:528 nt
	v_cvt_pk_bf16_f32 v20, v22, v23
	v_cvt_pk_bf16_f32 v21, v24, v25
	v_cvt_pk_bf16_f32 v22, v26, v27
	s_waitcnt lgkmcnt(0)
	v_add_f32_e32 v18, v18, v19
	ds_bpermute_b32 v19, v166, v18
	v_cvt_pk_bf16_f32 v23, v28, v29
	global_store_dwordx4 v[46:47], v[20:23], off offset:256
	s_and_saveexec_b64 s[8:9], s[4:5]
	s_cbranch_execz .LBB0_1012
	v_lshlrev_b64 v[20:21], 6, v[44:45]
	v_lshl_add_u64 v[20:21], s[76:77], 0, v[20:21]
	v_lshl_add_u64 v[20:21], s[70:71], 2, v[20:21]
	s_lshl_b32 s14, s56, 2
	v_lshl_add_u64 v[20:21], v[20:21], 0, s[14:15]
	s_waitcnt lgkmcnt(0)
	v_add_f32_e32 v18, v18, v19
	global_store_dword v[20:21], v18, off

.LBB0_1021:
	s_or_b64 exec, exec, s[8:9]
	s_waitcnt lgkmcnt(0)
	v_add_u32_e32 v19, 0xffffbc00, v28
	v_cmp_gt_i32_e64 s[8:9], s87, v28
	v_mov_b32_e32 v36, s27
	v_lshlrev_b64 v[30:31], 11, v[28:29]
	v_cndmask_b32_e64 v34, v19, v28, s[8:9]
	v_mov_b32_e32 v19, s63
	v_cndmask_b32_e64 v35, 0, v29, s[8:9]
	v_cndmask_b32_e64 v37, v19, v36, s[8:9]
	v_mov_b32_e32 v19, s62
	v_mov_b32_e32 v36, s26
	v_cndmask_b32_e64 v36, v19, v36, s[8:9]
	v_lshlrev_b64 v[34:35], 12, v[34:35]
	v_lshl_add_u64 v[34:35], v[36:37], 0, v[34:35]
	s_waitcnt vmcnt(1)
	v_pk_fma_f32 v[16:17], v[16:17], 0.5, v[26:27] op_sel_hi:[1,0,1]
	v_pk_fma_f32 v[14:15], v[14:15], 0.5, v[24:25] op_sel_hi:[1,0,1]
	s_waitcnt vmcnt(0)
	v_pk_fma_f32 v[12:13], v[12:13], 0.5, v[22:23] op_sel_hi:[1,0,1]
	v_pk_fma_f32 v[10:11], v[10:11], 0.5, v[20:21] op_sel_hi:[1,0,1]
	v_lshl_add_u64 v[24:25], s[88:89], 0, v[30:31]
	v_lshl_add_u64 v[26:27], v[160:161], 2, v[34:35]
	v_cvt_pk_bf16_f32 v20, v14, v15
	v_cvt_pk_bf16_f32 v21, v16, v17
	v_cvt_pk_bf16_f32 v22, v10, v11
	v_cvt_pk_bf16_f32 v23, v12, v13
	v_lshl_add_u64 v[30:31], v[160:161], 1, v[24:25]
	global_store_dwordx4 v[26:27], v[14:17], off nt
	global_store_dwordx4 v[26:27], v[10:13], off offset:16 nt
	global_store_dwordx4 v[30:31], v[20:23], off
	v_mov_b32_e32 v19, 0
	v_mov_b32_e32 v24, 0
	v_mov_b32_e32 v20, 0
	v_mov_b32_e32 v21, 0
	v_mov_b32_e32 v22, 0
	v_mov_b32_e32 v23, 0
	v_mov_b32_e32 v25, 0
	s_and_saveexec_b64 s[8:9], vcc
	s_cbranch_execz .LBB0_1023
	global_load_dwordx4 v[18:21], v[32:33], off offset:512 nt
	global_load_dwordx4 v[22:25], v[32:33], off offset:528 nt
.LBB0_1023:
	s_or_b64 exec, exec, s[8:9]
	v_mul_f32_e32 v15, v15, v15
	v_mul_f32_e32 v11, v11, v11
	v_fmac_f32_e32 v15, v14, v14
	v_mul_f32_e32 v14, v17, v17
	v_fmac_f32_e32 v11, v10, v10
	v_mul_f32_e32 v10, v13, v13
	v_fmac_f32_e32 v14, v16, v16
	v_fmac_f32_e32 v10, v12, v12
	v_add_f32_e32 v14, v15, v14
	v_add_f32_e32 v10, v11, v10
	s_waitcnt vmcnt(1)
	v_pk_fma_f32 v[8:9], v[8:9], 0.5, v[20:21] op_sel_hi:[1,0,1]
	v_pk_fma_f32 v[6:7], v[6:7], 0.5, v[18:19] op_sel_hi:[1,0,1]
	v_add_f32_e32 v14, v14, v10
	s_waitcnt vmcnt(0)
	v_pk_fma_f32 v[10:11], v[2:3], 0.5, v[22:23] op_sel_hi:[1,0,1]
	v_mul_f32_e32 v2, v7, v7
	v_mul_f32_e32 v3, v9, v9
	v_pk_fma_f32 v[12:13], v[4:5], 0.5, v[24:25] op_sel_hi:[1,0,1]
	v_fmac_f32_e32 v2, v6, v6
	v_fmac_f32_e32 v3, v8, v8
	v_add_f32_e32 v2, v2, v3
	v_mul_f32_e32 v3, v11, v11
	v_mul_f32_e32 v4, v13, v13
	v_fmac_f32_e32 v3, v10, v10
	v_fmac_f32_e32 v4, v12, v12
	v_add_f32_e32 v3, v3, v4
	v_add_f32_e32 v2, v2, v3
	v_add_f32_e32 v2, v14, v2
	ds_bpermute_b32 v3, v167, v2
	global_store_dwordx4 v[26:27], v[6:9], off offset:512 nt
	global_store_dwordx4 v[26:27], v[10:13], off offset:528 nt
	v_cvt_pk_bf16_f32 v4, v6, v7
	v_cvt_pk_bf16_f32 v5, v8, v9
	v_cvt_pk_bf16_f32 v6, v10, v11
	s_waitcnt lgkmcnt(0)
	v_add_f32_e32 v2, v2, v3
	ds_bpermute_b32 v3, v166, v2
	v_cvt_pk_bf16_f32 v7, v12, v13
	global_store_dwordx4 v[30:31], v[4:7], off offset:256
	s_and_saveexec_b64 s[8:9], s[4:5]
	s_cbranch_execz .LBB0_1025
	v_lshlrev_b64 v[4:5], 6, v[28:29]
	v_lshl_add_u64 v[4:5], s[76:77], 0, v[4:5]
	v_lshl_add_u64 v[4:5], s[70:71], 2, v[4:5]
	s_lshl_b32 s14, s56, 2
	v_lshl_add_u64 v[4:5], v[4:5], 0, s[14:15]
	s_waitcnt lgkmcnt(0)
	v_add_f32_e32 v2, v2, v3
	global_store_dword v[4:5], v2, off
